# attention step: QK fragment LDS reads issued before the next tile's global loads
# baseline (speedup 1.0000x reference)
.LBB0_309:
	v_lshl_add_u64 v[2:3], s[30:31], 0, v[190:191]
	v_lshl_add_u64 v[10:11], s[30:31], 0, v[188:189]
	v_add_co_u32_e32 v6, vcc, 0x13481000, v2
	s_nop 1
	v_addc_co_u32_e32 v7, vcc, 0, v3, vcc
	v_add_co_u32_e32 v12, vcc, 0x1f400000, v10
	global_load_dwordx4 v[2:5], v[6:7], off
	s_nop 0
	global_load_dwordx4 v[6:9], v[6:7], off offset:256
	v_addc_co_u32_e32 v13, vcc, 0, v11, vcc
	v_add_co_u32_e32 v176, vcc, 0x1f480000, v10
	s_nop 1
	v_addc_co_u32_e32 v177, vcc, 0, v11, vcc
	global_load_dwordx4 v[10:13], v[12:13], off offset:64
	s_nop 0
	global_load_dwordx4 v[176:179], v[176:177], off offset:64
	s_sub_i32 s73, 0, s73
	v_add_u32_e32 v0, s73, v213
	s_add_i32 s77, s77, 1
	s_waitcnt vmcnt(3)
	ds_write_b128 v0, v[2:5] offset:37888
	s_waitcnt vmcnt(2)
	ds_write_b128 v0, v[6:9] offset:46592
	v_add_u32_e32 v0, s73, v214
	s_mov_b64 vcc, 0x80000
	v_add_u32_e32 v2, 0xd800, v0
	v_add_u32_e32 v0, 0x10000, v0
	v_lshl_add_u64 v[188:189], v[188:189], 0, 64
	s_cmp_eq_u32 s79, s77
	v_lshl_add_u64 v[190:191], v[190:191], 0, vcc
	s_waitcnt vmcnt(1)
	ds_write2_b64 v2, v[10:11], v[12:13] offset1:2
	s_waitcnt vmcnt(0)
	ds_write2_b64 v0, v[176:177], v[178:179] offset1:2

.Lat_nostag:
	s_bitcmp1_b32 s77, 0
	s_cselect_b32 s73, 0x9400, 0
	s_cmp_gt_u32 s77, s49
	s_cbranch_scc1 .LBB0_309
	s_add_i32 vcc_lo, s73, 0
	s_add_i32 vcc_hi, vcc_lo, s78
	v_add3_u32 v0, vcc_hi, v211, v209
	v_add_u32_e32 v14, v210, v209
	ds_read_b128 v[144:147], v0
	ds_read_b128 v[160:163], v0 offset:32
	ds_read_b128 v[148:151], v14
	ds_read_b128 v[164:167], v14 offset:32
	ds_read_b128 v[216:219], v0 offset:64
	ds_read_b128 v[220:223], v0 offset:96
	ds_read_b128 v[224:227], v14 offset:64
	ds_read_b128 v[228:231], v14 offset:96
	v_add_u32_e32 v250, vcc_lo, v212
	v_lshl_add_u64 v[2:3], s[30:31], 0, v[190:191]
	v_lshl_add_u64 v[10:11], s[30:31], 0, v[188:189]
	v_add_co_u32_e32 v6, vcc, 0x13481000, v2
	s_nop 1
	v_addc_co_u32_e32 v7, vcc, 0, v3, vcc
	v_add_co_u32_e32 v12, vcc, 0x1f400000, v10
	global_load_dwordx4 v[2:5], v[6:7], off
	s_nop 0
	global_load_dwordx4 v[6:9], v[6:7], off offset:256
	v_addc_co_u32_e32 v13, vcc, 0, v11, vcc
	v_add_co_u32_e32 v176, vcc, 0x1f480000, v10
	s_nop 1
	v_addc_co_u32_e32 v177, vcc, 0, v11, vcc
	global_load_dwordx4 v[10:13], v[12:13], off offset:64
	s_nop 0
	global_load_dwordx4 v[176:179], v[176:177], off offset:64
	s_waitcnt lgkmcnt(5)
	v_mfma_f32_32x32x16_bf16 v[144:159], v[144:147], v[148:151], 0
	s_waitcnt lgkmcnt(4)
	v_mfma_f32_32x32x16_bf16 v[160:175], v[160:163], v[164:167], 0
	s_waitcnt lgkmcnt(1)
	v_mfma_f32_32x32x16_bf16 v[144:159], v[216:219], v[224:227], v[144:159]
	ds_read_b128 v[216:219], v0 offset:128
	ds_read_b128 v[224:227], v0 offset:160
	ds_read_b128 v[232:235], v14 offset:128
	ds_read_b128 v[236:239], v14 offset:160
	ds_read_b128 v[240:243], v0 offset:192
	ds_read_b128 v[244:247], v0 offset:224
	ds_read_b128 v[180:183], v14 offset:192
	ds_read_b128 v[184:187], v14 offset:224
	s_waitcnt lgkmcnt(8)
	v_mfma_f32_32x32x16_bf16 v[160:175], v[220:223], v[228:231], v[160:175]
	s_waitcnt lgkmcnt(5)
	v_mfma_f32_32x32x16_bf16 v[144:159], v[216:219], v[232:235], v[144:159]
	s_waitcnt lgkmcnt(4)
	v_mfma_f32_32x32x16_bf16 v[160:175], v[224:227], v[236:239], v[160:175]
	s_waitcnt lgkmcnt(1)
	v_mfma_f32_32x32x16_bf16 v[144:159], v[240:243], v[180:183], v[144:159]
	s_waitcnt lgkmcnt(0)
	v_mfma_f32_32x32x16_bf16 v[160:175], v[244:247], v[184:187], v[160:175]
	s_nop 11
	v_pk_add_f32 v[14:15], v[158:159], v[174:175]
	v_add_u32_e32 v174, v250, v208
	v_pk_add_f32 v[166:167], v[150:151], v[166:167]
	v_pk_add_f32 v[164:165], v[148:149], v[164:165]
	v_pk_add_f32 v[162:163], v[146:147], v[162:163]
	v_pk_add_f32 v[160:161], v[144:145], v[160:161]
	ds_read_b128 v[148:151], v174 offset:17408
	ds_read_b128 v[144:147], v174 offset:17440
	v_pk_add_f32 v[172:173], v[156:157], v[172:173]
	v_pk_add_f32 v[170:171], v[154:155], v[170:171]
	v_pk_add_f32 v[168:169], v[152:153], v[168:169]
	ds_read_b128 v[156:159], v174 offset:19968
	ds_read_b128 v[152:155], v174 offset:20000
	s_cmp_lg_u32 s49, s77
	s_cbranch_scc1 .LBB0_313
	v_cndmask_b32_e64 v0, v160, v202, s[90:91]
	v_cndmask_b32_e64 v161, v202, v161, s[88:89]
	v_cndmask_b32_e64 v160, v0, v160, s[88:89]
	v_cndmask_b32_e64 v162, v162, v202, s[92:93]
	v_cndmask_b32_e64 v163, v163, v202, s[94:95]
	v_cndmask_b32_e64 v164, v164, v202, s[96:97]
	v_cndmask_b32_e64 v165, v165, v202, s[4:5]
	v_cndmask_b32_e64 v166, v166, v202, s[6:7]
	v_cndmask_b32_e64 v167, v167, v202, s[8:9]
	v_cndmask_b32_e64 v168, v168, v202, s[10:11]
	v_cndmask_b32_e64 v169, v169, v202, s[12:13]
	v_cndmask_b32_e64 v170, v170, v202, s[14:15]
	v_cndmask_b32_e64 v171, v171, v202, s[16:17]
	v_cndmask_b32_e64 v172, v172, v202, s[18:19]
	v_cndmask_b32_e64 v173, v173, v202, s[20:21]
	v_cndmask_b32_e64 v14, v14, v202, s[22:23]
	v_cndmask_b32_e64 v15, v15, v202, s[24:25]
